# retention state scan: wait counts made of the younger loads only (independent of store retirement order)
# baseline (speedup 1.0000x reference)
.LBB0_557:
	global_load_dwordx2 v[70:71], v[14:15], off
	v_lshl_add_u64 v[14:15], v[14:15], 0, s[12:13]
	global_load_dwordx2 v[72:73], v[14:15], off
	v_lshl_add_u64 v[14:15], v[14:15], 0, s[12:13]
	global_load_dwordx2 v[74:75], v[14:15], off
	v_lshl_add_u64 v[14:15], v[14:15], 0, s[12:13]
	global_load_dwordx2 v[76:77], v[14:15], off
	v_lshl_add_u64 v[14:15], v[14:15], 0, s[12:13]
	global_load_dwordx2 v[78:79], v[14:15], off
	v_lshl_add_u64 v[14:15], v[14:15], 0, s[12:13]
	global_load_dwordx2 v[80:81], v[14:15], off
	v_lshl_add_u64 v[14:15], v[14:15], 0, s[12:13]
	global_load_dwordx2 v[82:83], v[14:15], off
	v_lshl_add_u64 v[14:15], v[14:15], 0, s[12:13]
	global_load_dwordx2 v[84:85], v[14:15], off
	v_lshl_add_u64 v[14:15], v[14:15], 0, s[12:13]
	global_load_dwordx2 v[86:87], v[14:15], off
	v_lshl_add_u64 v[14:15], v[14:15], 0, s[12:13]
	global_load_dwordx2 v[88:89], v[14:15], off
	v_lshl_add_u64 v[14:15], v[14:15], 0, s[12:13]
	global_load_dwordx2 v[90:91], v[14:15], off
	v_lshl_add_u64 v[14:15], v[14:15], 0, s[12:13]
	global_load_dwordx2 v[92:93], v[14:15], off
	v_lshl_add_u64 v[14:15], v[14:15], 0, s[12:13]
	global_load_dwordx2 v[94:95], v[14:15], off
	v_lshl_add_u64 v[14:15], v[14:15], 0, s[12:13]
	global_load_dwordx2 v[96:97], v[14:15], off
	v_lshl_add_u64 v[14:15], v[14:15], 0, s[12:13]
	global_load_dwordx2 v[98:99], v[14:15], off
	v_lshl_add_u64 v[14:15], v[14:15], 0, s[12:13]
	global_load_dwordx2 v[100:101], v[14:15], off
	v_lshl_add_u64 v[14:15], v[14:15], 0, s[12:13]
	s_waitcnt vmcnt(15)
	v_cvt_pk_bf16_f32 v18, v10, v11
	v_cvt_pk_bf16_f32 v19, v12, v13
	global_store_dwordx2 v[16:17], v[18:19], off
	v_lshl_add_u64 v[16:17], v[16:17], 0, s[12:13]
	v_lshlrev_b32_e32 v20, 16, v70
	v_and_b32_e32 v21, 0xffff0000, v70
	v_lshlrev_b32_e32 v22, 16, v71
	v_and_b32_e32 v23, 0xffff0000, v71
	v_pk_add_f32 v[10:11], v[10:11], v[20:21]
	v_pk_add_f32 v[12:13], v[12:13], v[22:23]
	v_pk_mul_f32 v[10:11], v[0:1], v[10:11]
	v_pk_mul_f32 v[12:13], v[0:1], v[12:13]
	s_waitcnt vmcnt(14)
	v_cvt_pk_bf16_f32 v18, v10, v11
	v_cvt_pk_bf16_f32 v19, v12, v13
	global_store_dwordx2 v[16:17], v[18:19], off
	v_lshl_add_u64 v[16:17], v[16:17], 0, s[12:13]
	v_lshlrev_b32_e32 v20, 16, v72
	v_and_b32_e32 v21, 0xffff0000, v72
	v_lshlrev_b32_e32 v22, 16, v73
	v_and_b32_e32 v23, 0xffff0000, v73
	v_pk_add_f32 v[10:11], v[10:11], v[20:21]
	v_pk_add_f32 v[12:13], v[12:13], v[22:23]
	v_pk_mul_f32 v[10:11], v[0:1], v[10:11]
	v_pk_mul_f32 v[12:13], v[0:1], v[12:13]
	s_waitcnt vmcnt(13)
	v_cvt_pk_bf16_f32 v18, v10, v11
	v_cvt_pk_bf16_f32 v19, v12, v13
	global_store_dwordx2 v[16:17], v[18:19], off
	v_lshl_add_u64 v[16:17], v[16:17], 0, s[12:13]
	v_lshlrev_b32_e32 v20, 16, v74
	v_and_b32_e32 v21, 0xffff0000, v74
	v_lshlrev_b32_e32 v22, 16, v75
	v_and_b32_e32 v23, 0xffff0000, v75
	v_pk_add_f32 v[10:11], v[10:11], v[20:21]
	v_pk_add_f32 v[12:13], v[12:13], v[22:23]
	v_pk_mul_f32 v[10:11], v[0:1], v[10:11]
	v_pk_mul_f32 v[12:13], v[0:1], v[12:13]
	s_waitcnt vmcnt(12)
	v_cvt_pk_bf16_f32 v18, v10, v11
	v_cvt_pk_bf16_f32 v19, v12, v13
	global_store_dwordx2 v[16:17], v[18:19], off
	v_lshl_add_u64 v[16:17], v[16:17], 0, s[12:13]
	v_lshlrev_b32_e32 v20, 16, v76
	v_and_b32_e32 v21, 0xffff0000, v76
	v_lshlrev_b32_e32 v22, 16, v77
	v_and_b32_e32 v23, 0xffff0000, v77
	v_pk_add_f32 v[10:11], v[10:11], v[20:21]
	v_pk_add_f32 v[12:13], v[12:13], v[22:23]
	v_pk_mul_f32 v[10:11], v[0:1], v[10:11]
	v_pk_mul_f32 v[12:13], v[0:1], v[12:13]
	s_waitcnt vmcnt(11)
	v_cvt_pk_bf16_f32 v18, v10, v11
	v_cvt_pk_bf16_f32 v19, v12, v13
	global_store_dwordx2 v[16:17], v[18:19], off
	v_lshl_add_u64 v[16:17], v[16:17], 0, s[12:13]
	v_lshlrev_b32_e32 v20, 16, v78
	v_and_b32_e32 v21, 0xffff0000, v78
	v_lshlrev_b32_e32 v22, 16, v79
	v_and_b32_e32 v23, 0xffff0000, v79
	v_pk_add_f32 v[10:11], v[10:11], v[20:21]
	v_pk_add_f32 v[12:13], v[12:13], v[22:23]
	v_pk_mul_f32 v[10:11], v[0:1], v[10:11]
	v_pk_mul_f32 v[12:13], v[0:1], v[12:13]
	s_waitcnt vmcnt(10)
	v_cvt_pk_bf16_f32 v18, v10, v11
	v_cvt_pk_bf16_f32 v19, v12, v13
	global_store_dwordx2 v[16:17], v[18:19], off
	v_lshl_add_u64 v[16:17], v[16:17], 0, s[12:13]
	v_lshlrev_b32_e32 v20, 16, v80
	v_and_b32_e32 v21, 0xffff0000, v80
	v_lshlrev_b32_e32 v22, 16, v81
	v_and_b32_e32 v23, 0xffff0000, v81
	v_pk_add_f32 v[10:11], v[10:11], v[20:21]
	v_pk_add_f32 v[12:13], v[12:13], v[22:23]
	v_pk_mul_f32 v[10:11], v[0:1], v[10:11]
	v_pk_mul_f32 v[12:13], v[0:1], v[12:13]
	s_waitcnt vmcnt(9)
	v_cvt_pk_bf16_f32 v18, v10, v11
	v_cvt_pk_bf16_f32 v19, v12, v13
	global_store_dwordx2 v[16:17], v[18:19], off
	v_lshl_add_u64 v[16:17], v[16:17], 0, s[12:13]
	v_lshlrev_b32_e32 v20, 16, v82
	v_and_b32_e32 v21, 0xffff0000, v82
	v_lshlrev_b32_e32 v22, 16, v83
	v_and_b32_e32 v23, 0xffff0000, v83
	v_pk_add_f32 v[10:11], v[10:11], v[20:21]
	v_pk_add_f32 v[12:13], v[12:13], v[22:23]
	v_pk_mul_f32 v[10:11], v[0:1], v[10:11]
	v_pk_mul_f32 v[12:13], v[0:1], v[12:13]
	s_waitcnt vmcnt(8)
	v_cvt_pk_bf16_f32 v18, v10, v11
	v_cvt_pk_bf16_f32 v19, v12, v13
	global_store_dwordx2 v[16:17], v[18:19], off
	v_lshl_add_u64 v[16:17], v[16:17], 0, s[12:13]
	v_lshlrev_b32_e32 v20, 16, v84
	v_and_b32_e32 v21, 0xffff0000, v84
	v_lshlrev_b32_e32 v22, 16, v85
	v_and_b32_e32 v23, 0xffff0000, v85
	v_pk_add_f32 v[10:11], v[10:11], v[20:21]
	v_pk_add_f32 v[12:13], v[12:13], v[22:23]
	v_pk_mul_f32 v[10:11], v[0:1], v[10:11]
	v_pk_mul_f32 v[12:13], v[0:1], v[12:13]
	s_waitcnt vmcnt(7)
	v_cvt_pk_bf16_f32 v18, v10, v11
	v_cvt_pk_bf16_f32 v19, v12, v13
	global_store_dwordx2 v[16:17], v[18:19], off
	v_lshl_add_u64 v[16:17], v[16:17], 0, s[12:13]
	v_lshlrev_b32_e32 v20, 16, v86
	v_and_b32_e32 v21, 0xffff0000, v86
	v_lshlrev_b32_e32 v22, 16, v87
	v_and_b32_e32 v23, 0xffff0000, v87
	v_pk_add_f32 v[10:11], v[10:11], v[20:21]
	v_pk_add_f32 v[12:13], v[12:13], v[22:23]
	v_pk_mul_f32 v[10:11], v[0:1], v[10:11]
	v_pk_mul_f32 v[12:13], v[0:1], v[12:13]
	s_waitcnt vmcnt(6)
	v_cvt_pk_bf16_f32 v18, v10, v11
	v_cvt_pk_bf16_f32 v19, v12, v13
	global_store_dwordx2 v[16:17], v[18:19], off
	v_lshl_add_u64 v[16:17], v[16:17], 0, s[12:13]
	v_lshlrev_b32_e32 v20, 16, v88
	v_and_b32_e32 v21, 0xffff0000, v88
	v_lshlrev_b32_e32 v22, 16, v89
	v_and_b32_e32 v23, 0xffff0000, v89
	v_pk_add_f32 v[10:11], v[10:11], v[20:21]
	v_pk_add_f32 v[12:13], v[12:13], v[22:23]
	v_pk_mul_f32 v[10:11], v[0:1], v[10:11]
	v_pk_mul_f32 v[12:13], v[0:1], v[12:13]
	s_waitcnt vmcnt(5)
	v_cvt_pk_bf16_f32 v18, v10, v11
	v_cvt_pk_bf16_f32 v19, v12, v13
	global_store_dwordx2 v[16:17], v[18:19], off
	v_lshl_add_u64 v[16:17], v[16:17], 0, s[12:13]
	v_lshlrev_b32_e32 v20, 16, v90
	v_and_b32_e32 v21, 0xffff0000, v90
	v_lshlrev_b32_e32 v22, 16, v91
	v_and_b32_e32 v23, 0xffff0000, v91
	v_pk_add_f32 v[10:11], v[10:11], v[20:21]
	v_pk_add_f32 v[12:13], v[12:13], v[22:23]
	v_pk_mul_f32 v[10:11], v[0:1], v[10:11]
	v_pk_mul_f32 v[12:13], v[0:1], v[12:13]
	s_waitcnt vmcnt(4)
	v_cvt_pk_bf16_f32 v18, v10, v11
	v_cvt_pk_bf16_f32 v19, v12, v13
	global_store_dwordx2 v[16:17], v[18:19], off
	v_lshl_add_u64 v[16:17], v[16:17], 0, s[12:13]
	v_lshlrev_b32_e32 v20, 16, v92
	v_and_b32_e32 v21, 0xffff0000, v92
	v_lshlrev_b32_e32 v22, 16, v93
	v_and_b32_e32 v23, 0xffff0000, v93
	v_pk_add_f32 v[10:11], v[10:11], v[20:21]
	v_pk_add_f32 v[12:13], v[12:13], v[22:23]
	v_pk_mul_f32 v[10:11], v[0:1], v[10:11]
	v_pk_mul_f32 v[12:13], v[0:1], v[12:13]
	s_waitcnt vmcnt(3)
	v_cvt_pk_bf16_f32 v18, v10, v11
	v_cvt_pk_bf16_f32 v19, v12, v13
	global_store_dwordx2 v[16:17], v[18:19], off
	v_lshl_add_u64 v[16:17], v[16:17], 0, s[12:13]
	v_lshlrev_b32_e32 v20, 16, v94
	v_and_b32_e32 v21, 0xffff0000, v94
	v_lshlrev_b32_e32 v22, 16, v95
	v_and_b32_e32 v23, 0xffff0000, v95
	v_pk_add_f32 v[10:11], v[10:11], v[20:21]
	v_pk_add_f32 v[12:13], v[12:13], v[22:23]
	v_pk_mul_f32 v[10:11], v[0:1], v[10:11]
	v_pk_mul_f32 v[12:13], v[0:1], v[12:13]
	s_waitcnt vmcnt(2)
	v_cvt_pk_bf16_f32 v18, v10, v11
	v_cvt_pk_bf16_f32 v19, v12, v13
	global_store_dwordx2 v[16:17], v[18:19], off
	v_lshl_add_u64 v[16:17], v[16:17], 0, s[12:13]
	v_lshlrev_b32_e32 v20, 16, v96
	v_and_b32_e32 v21, 0xffff0000, v96
	v_lshlrev_b32_e32 v22, 16, v97
	v_and_b32_e32 v23, 0xffff0000, v97
	v_pk_add_f32 v[10:11], v[10:11], v[20:21]
	v_pk_add_f32 v[12:13], v[12:13], v[22:23]
	v_pk_mul_f32 v[10:11], v[0:1], v[10:11]
	v_pk_mul_f32 v[12:13], v[0:1], v[12:13]
	s_waitcnt vmcnt(1)
	v_cvt_pk_bf16_f32 v18, v10, v11
	v_cvt_pk_bf16_f32 v19, v12, v13
	global_store_dwordx2 v[16:17], v[18:19], off
	v_lshl_add_u64 v[16:17], v[16:17], 0, s[12:13]
	v_lshlrev_b32_e32 v20, 16, v98
	v_and_b32_e32 v21, 0xffff0000, v98
	v_lshlrev_b32_e32 v22, 16, v99
	v_and_b32_e32 v23, 0xffff0000, v99
	v_pk_add_f32 v[10:11], v[10:11], v[20:21]
	v_pk_add_f32 v[12:13], v[12:13], v[22:23]
	v_pk_mul_f32 v[10:11], v[0:1], v[10:11]
	v_pk_mul_f32 v[12:13], v[0:1], v[12:13]
	s_waitcnt vmcnt(0)
	v_cvt_pk_bf16_f32 v18, v10, v11
	v_cvt_pk_bf16_f32 v19, v12, v13
	global_store_dwordx2 v[16:17], v[18:19], off
	v_lshl_add_u64 v[16:17], v[16:17], 0, s[12:13]
	v_lshlrev_b32_e32 v20, 16, v100
	v_and_b32_e32 v21, 0xffff0000, v100
	v_lshlrev_b32_e32 v22, 16, v101
	v_and_b32_e32 v23, 0xffff0000, v101
	v_pk_add_f32 v[10:11], v[10:11], v[20:21]
	v_pk_add_f32 v[12:13], v[12:13], v[22:23]
	v_pk_mul_f32 v[10:11], v[0:1], v[10:11]
	v_pk_mul_f32 v[12:13], v[0:1], v[12:13]
	s_add_i32 s0, s0, -1
	s_cmp_lg_u32 s0, 0
	s_cbranch_scc1 .LBB0_557
	v_readlane_b32 s0, v254, 11
	s_nop 1
	v_add_u32_e32 v8, s0, v8
	s_mov_b32 s0, 0x1ffff
	v_cmp_lt_i32_e32 vcc, s0, v8
	v_readlane_b32 s0, v254, 20
	s_or_b64 s[10:11], vcc, s[10:11]
	s_nop 0
	v_add_u32_e32 v9, s0, v9
	s_andn2_b64 exec, exec, s[10:11]
	s_cbranch_execnz .LBB0_556
